# combo15 + Swiglu epilogue: the eight RMS-scale row loads and their address math issued before the pre-epilogue workgroup barrier instead of after it
# speedup vs baseline: 1.0053x; 1.0017x over previous
.LBB0_290:
	s_add_u32 s26, s24, 0xfffc0080
	s_addc_u32 s27, s25, -1
	s_add_u32 s52, s24, 0xfffc0000
	s_addc_u32 s53, s25, -1
	s_mov_b32 m0, s43
	ds_read_b128 v[130:133], v188
	ds_read_b128 v[134:137], v188 offset:1024
	ds_read_b128 v[138:141], v188 offset:2048
	ds_read_b128 v[154:157], v188 offset:3072
	ds_read_b128 v[158:161], v188 offset:16384
	ds_read_b128 v[162:165], v188 offset:17408
	ds_read_b128 v[166:169], v188 offset:18432
	ds_read_b128 v[176:179], v188 offset:19456
	ds_read_b128 v[180:183], v175
	ds_read_b128 v[184:187], v175 offset:1024
	ds_read_b128 v[192:195], v175 offset:2048
	ds_read_b128 v[196:199], v175 offset:3072
	ds_read_b128 v[200:203], v175 offset:4096
	ds_read_b128 v[204:207], v175 offset:5120
	ds_read_b128 v[208:211], v175 offset:6144
	ds_read_b128 v[212:215], v175 offset:7168
	global_load_lds_dwordx4 v144, s[52:53]
	s_add_i32 m0, s38, 0xc000
	s_nop 0
	global_load_lds_dwordx4 v150, s[24:25]
	s_add_i32 m0, s38, 0xe000
	s_cmp_eq_u32 s50, 12
	global_load_lds_dwordx4 v152, s[24:25]
	s_cselect_b32 s29, s17, s27
	s_cselect_b32 s28, s46, s26
	s_cselect_b32 s27, s15, s49
	s_cselect_b32 s26, s47, s48
	s_waitcnt vmcnt(8)
	s_waitcnt lgkmcnt(0)
	s_barrier
	s_setprio 1
	s_waitcnt lgkmcnt(0)
	v_mfma_f32_16x16x32_bf16 v[126:129], v[130:133], v[180:183], v[126:129]
	v_mfma_f32_16x16x32_bf16 v[122:125], v[138:141], v[180:183], v[122:125]
	v_mfma_f32_16x16x32_bf16 v[110:113], v[130:133], v[192:195], v[110:113]
	v_mfma_f32_16x16x32_bf16 v[106:109], v[138:141], v[192:195], v[106:109]
	v_mfma_f32_16x16x32_bf16 v[94:97], v[130:133], v[200:203], v[94:97]
	v_mfma_f32_16x16x32_bf16 v[90:93], v[138:141], v[200:203], v[90:93]
	v_mfma_f32_16x16x32_bf16 v[78:81], v[130:133], v[208:211], v[78:81]
	v_mfma_f32_16x16x32_bf16 v[74:77], v[138:141], v[208:211], v[74:77]
	v_mfma_f32_16x16x32_bf16 v[126:129], v[134:137], v[184:187], v[126:129]
	v_mfma_f32_16x16x32_bf16 v[122:125], v[154:157], v[184:187], v[122:125]
	v_mfma_f32_16x16x32_bf16 v[110:113], v[134:137], v[196:199], v[110:113]
	v_mfma_f32_16x16x32_bf16 v[106:109], v[154:157], v[196:199], v[106:109]
	v_mfma_f32_16x16x32_bf16 v[94:97], v[134:137], v[204:207], v[94:97]
	v_mfma_f32_16x16x32_bf16 v[90:93], v[154:157], v[204:207], v[90:93]
	v_mfma_f32_16x16x32_bf16 v[78:81], v[134:137], v[212:215], v[78:81]
	v_mfma_f32_16x16x32_bf16 v[74:77], v[154:157], v[212:215], v[74:77]
	s_setprio 0
	s_setprio 1
	v_mfma_f32_16x16x32_bf16 v[118:121], v[158:161], v[180:183], v[118:121]
	v_mfma_f32_16x16x32_bf16 v[114:117], v[166:169], v[180:183], v[114:117]
	v_mfma_f32_16x16x32_bf16 v[102:105], v[158:161], v[192:195], v[102:105]
	v_mfma_f32_16x16x32_bf16 v[98:101], v[166:169], v[192:195], v[98:101]
	v_mfma_f32_16x16x32_bf16 v[86:89], v[158:161], v[200:203], v[86:89]
	v_mfma_f32_16x16x32_bf16 v[82:85], v[166:169], v[200:203], v[82:85]
	v_mfma_f32_16x16x32_bf16 v[70:73], v[158:161], v[208:211], v[70:73]
	v_mfma_f32_16x16x32_bf16 v[66:69], v[166:169], v[208:211], v[66:69]
	v_mfma_f32_16x16x32_bf16 v[118:121], v[162:165], v[184:187], v[118:121]
	v_mfma_f32_16x16x32_bf16 v[114:117], v[176:179], v[184:187], v[114:117]
	v_mfma_f32_16x16x32_bf16 v[102:105], v[162:165], v[196:199], v[102:105]
	v_mfma_f32_16x16x32_bf16 v[98:101], v[176:179], v[196:199], v[98:101]
	v_mfma_f32_16x16x32_bf16 v[86:89], v[162:165], v[204:207], v[86:89]
	v_mfma_f32_16x16x32_bf16 v[82:85], v[176:179], v[204:207], v[82:85]
	v_mfma_f32_16x16x32_bf16 v[70:73], v[162:165], v[212:215], v[70:73]
	v_mfma_f32_16x16x32_bf16 v[66:69], v[176:179], v[212:215], v[66:69]
	s_setprio 0
	s_barrier
	s_add_i32 s51, s36, 0x10000
	s_mov_b32 m0, s51
	ds_read_b128 v[180:183], v175 offset:16384
	ds_read_b128 v[184:187], v175 offset:17408
	ds_read_b128 v[192:195], v175 offset:18432
	ds_read_b128 v[196:199], v175 offset:19456
	ds_read_b128 v[200:203], v175 offset:20480
	ds_read_b128 v[204:207], v175 offset:21504
	ds_read_b128 v[208:211], v175 offset:22528
	ds_read_b128 v[212:215], v175 offset:23552
	global_load_lds_dwordx4 v0, s[26:27]
	s_add_i32 m0, s51, 0x2000
	s_add_u32 s52, s26, 0x40000
	global_load_lds_dwordx4 v142, s[26:27]
	s_addc_u32 s53, s27, 0
	s_add_i32 s51, s36, 0x14000
	s_mov_b32 m0, s51
	s_nop 0
	global_load_lds_dwordx4 v0, s[52:53]
	s_add_i32 m0, s51, 0x2000
	s_nop 0
	global_load_lds_dwordx4 v142, s[52:53]
	s_mov_b32 m0, s38
	s_nop 0
	global_load_lds_dwordx4 v146, s[28:29]
	s_waitcnt vmcnt(7)
	s_waitcnt lgkmcnt(0)
	s_barrier
	s_setprio 1
	s_waitcnt lgkmcnt(0)
	v_mfma_f32_16x16x32_bf16 v[62:65], v[130:133], v[180:183], v[62:65]
	v_mfma_f32_16x16x32_bf16 v[58:61], v[138:141], v[180:183], v[58:61]
	v_mfma_f32_16x16x32_bf16 v[46:49], v[130:133], v[192:195], v[46:49]
	v_mfma_f32_16x16x32_bf16 v[42:45], v[138:141], v[192:195], v[42:45]
	v_mfma_f32_16x16x32_bf16 v[30:33], v[130:133], v[200:203], v[30:33]
	v_mfma_f32_16x16x32_bf16 v[26:29], v[138:141], v[200:203], v[26:29]
	v_mfma_f32_16x16x32_bf16 v[14:17], v[130:133], v[208:211], v[14:17]
	v_mfma_f32_16x16x32_bf16 v[10:13], v[138:141], v[208:211], v[10:13]
	v_mfma_f32_16x16x32_bf16 v[62:65], v[134:137], v[184:187], v[62:65]
	v_mfma_f32_16x16x32_bf16 v[58:61], v[154:157], v[184:187], v[58:61]
	v_mfma_f32_16x16x32_bf16 v[46:49], v[134:137], v[196:199], v[46:49]
	v_mfma_f32_16x16x32_bf16 v[42:45], v[154:157], v[196:199], v[42:45]
	v_mfma_f32_16x16x32_bf16 v[30:33], v[134:137], v[204:207], v[30:33]
	v_mfma_f32_16x16x32_bf16 v[26:29], v[154:157], v[204:207], v[26:29]
	v_mfma_f32_16x16x32_bf16 v[14:17], v[134:137], v[212:215], v[14:17]
	v_mfma_f32_16x16x32_bf16 v[10:13], v[154:157], v[212:215], v[10:13]
	s_setprio 0
	s_setprio 1
	v_mfma_f32_16x16x32_bf16 v[54:57], v[158:161], v[180:183], v[54:57]
	v_mfma_f32_16x16x32_bf16 v[50:53], v[166:169], v[180:183], v[50:53]
	v_mfma_f32_16x16x32_bf16 v[38:41], v[158:161], v[192:195], v[38:41]
	v_mfma_f32_16x16x32_bf16 v[34:37], v[166:169], v[192:195], v[34:37]
	v_mfma_f32_16x16x32_bf16 v[22:25], v[158:161], v[200:203], v[22:25]
	v_mfma_f32_16x16x32_bf16 v[18:21], v[166:169], v[200:203], v[18:21]
	v_mfma_f32_16x16x32_bf16 v[6:9], v[158:161], v[208:211], v[6:9]
	v_mfma_f32_16x16x32_bf16 v[2:5], v[166:169], v[208:211], v[2:5]
	v_mfma_f32_16x16x32_bf16 v[54:57], v[162:165], v[184:187], v[54:57]
	v_mfma_f32_16x16x32_bf16 v[50:53], v[176:179], v[184:187], v[50:53]
	v_mfma_f32_16x16x32_bf16 v[38:41], v[162:165], v[196:199], v[38:41]
	v_mfma_f32_16x16x32_bf16 v[34:37], v[176:179], v[196:199], v[34:37]
	v_mfma_f32_16x16x32_bf16 v[22:25], v[162:165], v[204:207], v[22:25]
	v_mfma_f32_16x16x32_bf16 v[18:21], v[176:179], v[204:207], v[18:21]
	v_mfma_f32_16x16x32_bf16 v[6:9], v[162:165], v[212:215], v[6:9]
	v_mfma_f32_16x16x32_bf16 v[2:5], v[176:179], v[212:215], v[2:5]
	s_setprio 0
	s_barrier
	s_mov_b32 m0, s39
	ds_read_b128 v[130:133], v188 offset:32768
	ds_read_b128 v[134:137], v188 offset:33792
	ds_read_b128 v[138:141], v188 offset:34816
	ds_read_b128 v[154:157], v188 offset:35840
	ds_read_b128 v[158:161], v188 offset:49152
	ds_read_b128 v[162:165], v188 offset:50176
	ds_read_b128 v[166:169], v188 offset:51200
	ds_read_b128 v[176:179], v188 offset:52224
	ds_read_b128 v[180:183], v175 offset:32768
	ds_read_b128 v[184:187], v175 offset:33792
	ds_read_b128 v[192:195], v175 offset:34816
	ds_read_b128 v[196:199], v175 offset:35840
	ds_read_b128 v[200:203], v175 offset:36864
	ds_read_b128 v[204:207], v175 offset:37888
	ds_read_b128 v[208:211], v175 offset:38912
	ds_read_b128 v[212:215], v175 offset:39936
	global_load_lds_dwordx4 v144, s[28:29]
	s_add_u32 s28, s28, 0x40000
	s_addc_u32 s29, s29, 0
	s_mov_b32 m0, s40
	s_nop 0
	global_load_lds_dwordx4 v146, s[28:29]
	s_mov_b32 m0, s41
	s_nop 0
	global_load_lds_dwordx4 v144, s[28:29]
	s_waitcnt vmcnt(8)
	s_waitcnt lgkmcnt(0)
	s_barrier
	s_setprio 1
	s_waitcnt lgkmcnt(0)
	v_mfma_f32_16x16x32_bf16 v[126:129], v[130:133], v[180:183], v[126:129]
	v_mfma_f32_16x16x32_bf16 v[122:125], v[138:141], v[180:183], v[122:125]
	v_mfma_f32_16x16x32_bf16 v[110:113], v[130:133], v[192:195], v[110:113]
	v_mfma_f32_16x16x32_bf16 v[106:109], v[138:141], v[192:195], v[106:109]
	v_mfma_f32_16x16x32_bf16 v[94:97], v[130:133], v[200:203], v[94:97]
	v_mfma_f32_16x16x32_bf16 v[90:93], v[138:141], v[200:203], v[90:93]
	v_mfma_f32_16x16x32_bf16 v[78:81], v[130:133], v[208:211], v[78:81]
	v_mfma_f32_16x16x32_bf16 v[74:77], v[138:141], v[208:211], v[74:77]
	v_mfma_f32_16x16x32_bf16 v[126:129], v[134:137], v[184:187], v[126:129]
	v_mfma_f32_16x16x32_bf16 v[122:125], v[154:157], v[184:187], v[122:125]
	v_mfma_f32_16x16x32_bf16 v[110:113], v[134:137], v[196:199], v[110:113]
	v_mfma_f32_16x16x32_bf16 v[106:109], v[154:157], v[196:199], v[106:109]
	v_mfma_f32_16x16x32_bf16 v[94:97], v[134:137], v[204:207], v[94:97]
	v_mfma_f32_16x16x32_bf16 v[90:93], v[154:157], v[204:207], v[90:93]
	v_mfma_f32_16x16x32_bf16 v[78:81], v[134:137], v[212:215], v[78:81]
	v_mfma_f32_16x16x32_bf16 v[74:77], v[154:157], v[212:215], v[74:77]
	s_setprio 0
	s_setprio 1
	v_mfma_f32_16x16x32_bf16 v[118:121], v[158:161], v[180:183], v[118:121]
	v_mfma_f32_16x16x32_bf16 v[114:117], v[166:169], v[180:183], v[114:117]
	v_mfma_f32_16x16x32_bf16 v[102:105], v[158:161], v[192:195], v[102:105]
	v_mfma_f32_16x16x32_bf16 v[98:101], v[166:169], v[192:195], v[98:101]
	v_mfma_f32_16x16x32_bf16 v[86:89], v[158:161], v[200:203], v[86:89]
	v_mfma_f32_16x16x32_bf16 v[82:85], v[166:169], v[200:203], v[82:85]
	v_mfma_f32_16x16x32_bf16 v[70:73], v[158:161], v[208:211], v[70:73]
	v_mfma_f32_16x16x32_bf16 v[66:69], v[166:169], v[208:211], v[66:69]
	v_mfma_f32_16x16x32_bf16 v[118:121], v[162:165], v[184:187], v[118:121]
	v_mfma_f32_16x16x32_bf16 v[114:117], v[176:179], v[184:187], v[114:117]
	v_mfma_f32_16x16x32_bf16 v[102:105], v[162:165], v[196:199], v[102:105]
	v_mfma_f32_16x16x32_bf16 v[98:101], v[176:179], v[196:199], v[98:101]
	v_mfma_f32_16x16x32_bf16 v[86:89], v[162:165], v[204:207], v[86:89]
	v_mfma_f32_16x16x32_bf16 v[82:85], v[176:179], v[204:207], v[82:85]
	v_mfma_f32_16x16x32_bf16 v[70:73], v[162:165], v[212:215], v[70:73]
	v_mfma_f32_16x16x32_bf16 v[66:69], v[176:179], v[212:215], v[66:69]
	s_setprio 0
	s_barrier
	s_add_u32 s26, s26, 0x80
	s_addc_u32 s27, s27, 0
	s_add_i32 s51, s36, 0x18000
	s_mov_b32 m0, s51
	ds_read_b128 v[180:183], v175 offset:49152
	ds_read_b128 v[184:187], v175 offset:50176
	ds_read_b128 v[192:195], v175 offset:51200
	ds_read_b128 v[196:199], v175 offset:52224
	ds_read_b128 v[200:203], v175 offset:53248
	ds_read_b128 v[204:207], v175 offset:54272
	ds_read_b128 v[208:211], v175 offset:55296
	ds_read_b128 v[212:215], v175 offset:56320
	global_load_lds_dwordx4 v0, s[26:27]
	s_add_i32 m0, s51, 0x2000
	s_add_u32 s52, s26, 0x40000
	global_load_lds_dwordx4 v142, s[26:27]
	s_addc_u32 s53, s27, 0
	s_add_i32 s51, s36, 0x1c000
	s_mov_b32 m0, s51
	s_add_u32 s28, s28, 0xfffc0080
	global_load_lds_dwordx4 v0, s[52:53]
	s_addc_u32 s29, s29, -1
	s_add_i32 m0, s51, 0x2000
	s_nop 0
	global_load_lds_dwordx4 v142, s[52:53]
	s_mov_b32 m0, s42
	s_nop 0
	global_load_lds_dwordx4 v146, s[28:29]
	s_waitcnt vmcnt(7)
	s_waitcnt lgkmcnt(0)
	s_barrier
	s_setprio 1
	s_waitcnt lgkmcnt(0)
	v_mfma_f32_16x16x32_bf16 v[62:65], v[130:133], v[180:183], v[62:65]
	v_mfma_f32_16x16x32_bf16 v[58:61], v[138:141], v[180:183], v[58:61]
	v_mfma_f32_16x16x32_bf16 v[46:49], v[130:133], v[192:195], v[46:49]
	v_mfma_f32_16x16x32_bf16 v[42:45], v[138:141], v[192:195], v[42:45]
	v_mfma_f32_16x16x32_bf16 v[30:33], v[130:133], v[200:203], v[30:33]
	v_mfma_f32_16x16x32_bf16 v[26:29], v[138:141], v[200:203], v[26:29]
	v_mfma_f32_16x16x32_bf16 v[14:17], v[130:133], v[208:211], v[14:17]
	v_mfma_f32_16x16x32_bf16 v[10:13], v[138:141], v[208:211], v[10:13]
	v_mfma_f32_16x16x32_bf16 v[62:65], v[134:137], v[184:187], v[62:65]
	v_mfma_f32_16x16x32_bf16 v[58:61], v[154:157], v[184:187], v[58:61]
	v_mfma_f32_16x16x32_bf16 v[46:49], v[134:137], v[196:199], v[46:49]
	v_mfma_f32_16x16x32_bf16 v[42:45], v[154:157], v[196:199], v[42:45]
	v_mfma_f32_16x16x32_bf16 v[30:33], v[134:137], v[204:207], v[30:33]
	v_mfma_f32_16x16x32_bf16 v[26:29], v[154:157], v[204:207], v[26:29]
	v_mfma_f32_16x16x32_bf16 v[14:17], v[134:137], v[212:215], v[14:17]
	v_mfma_f32_16x16x32_bf16 v[10:13], v[154:157], v[212:215], v[10:13]
	s_setprio 0
	s_setprio 1
	v_mfma_f32_16x16x32_bf16 v[54:57], v[158:161], v[180:183], v[54:57]
	v_mfma_f32_16x16x32_bf16 v[50:53], v[166:169], v[180:183], v[50:53]
	v_mfma_f32_16x16x32_bf16 v[38:41], v[158:161], v[192:195], v[38:41]
	v_mfma_f32_16x16x32_bf16 v[34:37], v[166:169], v[192:195], v[34:37]
	v_mfma_f32_16x16x32_bf16 v[22:25], v[158:161], v[200:203], v[22:25]
	v_mfma_f32_16x16x32_bf16 v[18:21], v[166:169], v[200:203], v[18:21]
	v_mfma_f32_16x16x32_bf16 v[6:9], v[158:161], v[208:211], v[6:9]
	v_mfma_f32_16x16x32_bf16 v[2:5], v[166:169], v[208:211], v[2:5]
	v_mfma_f32_16x16x32_bf16 v[54:57], v[162:165], v[184:187], v[54:57]
	v_mfma_f32_16x16x32_bf16 v[50:53], v[176:179], v[184:187], v[50:53]
	v_mfma_f32_16x16x32_bf16 v[38:41], v[162:165], v[196:199], v[38:41]
	v_mfma_f32_16x16x32_bf16 v[34:37], v[176:179], v[196:199], v[34:37]
	v_mfma_f32_16x16x32_bf16 v[22:25], v[162:165], v[204:207], v[22:25]
	v_mfma_f32_16x16x32_bf16 v[18:21], v[176:179], v[204:207], v[18:21]
	v_mfma_f32_16x16x32_bf16 v[6:9], v[162:165], v[212:215], v[6:9]
	v_mfma_f32_16x16x32_bf16 v[2:5], v[176:179], v[212:215], v[2:5]
	s_setprio 0
	s_barrier
	s_add_i32 s50, s50, 2
	s_add_u32 s24, s24, 0x100
	s_addc_u32 s25, s25, 0
	s_add_u32 s48, s48, 0x100
	s_addc_u32 s49, s49, 0
	s_cmp_gt_u32 s50, 13
	s_cbranch_scc0 .LBB0_290
	v_lshl_add_u32 v168, s22, 8, v172
	v_ashrrev_i32_e32 v169, 31, v168
	v_lshlrev_b64 v[130:131], 6, v[168:169]
	v_lshl_add_u64 v[130:131], v[148:149], 0, v[130:131]
	global_load_dwordx4 v[176:179], v[130:131], off
	v_or_b32_e32 v166, 16, v168
	v_ashrrev_i32_e32 v167, 31, v166
	v_lshlrev_b64 v[130:131], 6, v[166:167]
	v_lshl_add_u64 v[130:131], v[148:149], 0, v[130:131]
	global_load_dwordx4 v[180:183], v[130:131], off
	v_or_b32_e32 v164, 32, v168
	v_ashrrev_i32_e32 v165, 31, v164
	v_lshlrev_b64 v[130:131], 6, v[164:165]
	v_lshl_add_u64 v[130:131], v[148:149], 0, v[130:131]
	global_load_dwordx4 v[184:187], v[130:131], off
	v_or_b32_e32 v162, 48, v168
	v_ashrrev_i32_e32 v163, 31, v162
	v_lshlrev_b64 v[130:131], 6, v[162:163]
	v_lshl_add_u64 v[130:131], v[148:149], 0, v[130:131]
	global_load_dwordx4 v[192:195], v[130:131], off
	v_add_u32_e32 v160, 0x80, v168
	v_ashrrev_i32_e32 v161, 31, v160
	v_lshlrev_b64 v[130:131], 6, v[160:161]
	v_add_u32_e32 v158, 0x90, v168
	v_lshl_add_u64 v[130:131], v[148:149], 0, v[130:131]
	v_ashrrev_i32_e32 v159, 31, v158
	global_load_dwordx4 v[196:199], v[130:131], off
	v_lshlrev_b64 v[130:131], 6, v[158:159]
	v_add_u32_e32 v156, 0xa0, v168
	v_lshl_add_u64 v[130:131], v[148:149], 0, v[130:131]
	v_ashrrev_i32_e32 v157, 31, v156
	global_load_dwordx4 v[138:141], v[130:131], off
	v_lshlrev_b64 v[130:131], 6, v[156:157]
	v_add_u32_e32 v154, 0xb0, v168
	v_lshl_add_u64 v[130:131], v[148:149], 0, v[130:131]
	v_ashrrev_i32_e32 v155, 31, v154
	global_load_dwordx4 v[134:137], v[130:131], off
	v_lshlrev_b64 v[130:131], 6, v[154:155]
	v_lshl_add_u64 v[130:131], v[148:149], 0, v[130:131]
	global_load_dwordx4 v[130:133], v[130:131], off
	s_and_b64 vcc, exec, s[12:13]
	s_cbranch_vccz .LBB0_293
	s_barrier
.LBB0_293:
	v_cmp_lt_i32_e32 vcc, v239, v244
	v_lshl_or_b32 v170, s23, 7, v174
	v_ashrrev_i32_e32 v171, 31, v170
	v_cndmask_b32_e32 v155, v234, v239, vcc
	v_cmp_lt_i32_e32 vcc, v240, v244
	v_lshlrev_b32_e32 v163, 2, v155
	v_pk_mul_f32 v[116:117], v[124:125], v[116:117]
	v_cndmask_b32_e32 v155, v234, v240, vcc
	v_lshlrev_b32_e32 v165, 2, v155
	v_pk_mul_f32 v[114:115], v[122:123], v[114:115]
	v_pk_mul_f32 v[120:121], v[128:129], v[120:121]
	v_pk_mul_f32 v[118:119], v[126:127], v[118:119]
	v_pk_mul_f32 v[100:101], v[108:109], v[100:101]
	v_pk_mul_f32 v[98:99], v[106:107], v[98:99]
	v_pk_mul_f32 v[104:105], v[112:113], v[104:105]
	v_pk_mul_f32 v[102:103], v[110:111], v[102:103]
	v_pk_mul_f32 v[84:85], v[92:93], v[84:85]
	v_pk_mul_f32 v[82:83], v[90:91], v[82:83]
	v_pk_mul_f32 v[88:89], v[96:97], v[88:89]
	v_pk_mul_f32 v[86:87], v[94:95], v[86:87]
	v_pk_mul_f32 v[68:69], v[76:77], v[68:69]
	v_pk_mul_f32 v[66:67], v[74:75], v[66:67]
	v_pk_mul_f32 v[72:73], v[80:81], v[72:73]
	v_pk_mul_f32 v[70:71], v[78:79], v[70:71]
	v_pk_mul_f32 v[52:53], v[60:61], v[52:53]
	v_pk_mul_f32 v[50:51], v[58:59], v[50:51]
	v_pk_mul_f32 v[56:57], v[64:65], v[56:57]
	v_pk_mul_f32 v[54:55], v[62:63], v[54:55]
	v_pk_mul_f32 v[36:37], v[44:45], v[36:37]
	v_pk_mul_f32 v[34:35], v[42:43], v[34:35]
	v_pk_mul_f32 v[40:41], v[48:49], v[40:41]
	v_pk_mul_f32 v[38:39], v[46:47], v[38:39]
	v_pk_mul_f32 v[20:21], v[28:29], v[20:21]
	v_pk_mul_f32 v[18:19], v[26:27], v[18:19]
	v_pk_mul_f32 v[24:25], v[32:33], v[24:25]
	v_pk_mul_f32 v[22:23], v[30:31], v[22:23]
	v_pk_mul_f32 v[4:5], v[12:13], v[4:5]
	v_pk_mul_f32 v[2:3], v[10:11], v[2:3]
	v_pk_mul_f32 v[8:9], v[16:17], v[8:9]
	v_pk_mul_f32 v[6:7], v[14:15], v[6:7]
	s_andn2_b64 vcc, exec, s[6:7]
	s_waitcnt vmcnt(0)
	v_add_f32_e32 v176, v176, v177
	v_add_f32_e32 v178, v178, v179
	v_add_f32_e32 v180, v180, v181
	v_add_f32_e32 v182, v182, v183
	v_add_f32_e32 v184, v184, v185
	v_add_f32_e32 v186, v186, v187
	v_add_f32_e32 v192, v192, v193
	v_add_f32_e32 v194, v194, v195
	v_add_f32_e32 v176, v176, v178
	v_add_f32_e32 v180, v180, v182
	v_add_f32_e32 v184, v184, v186
	v_add_f32_e32 v192, v192, v194
	ds_bpermute_b32 v177, v163, v176
	ds_bpermute_b32 v181, v163, v180
	ds_bpermute_b32 v185, v163, v184
	ds_bpermute_b32 v193, v163, v192
	s_waitcnt lgkmcnt(3)
	v_add_f32_e32 v176, v176, v177
	ds_bpermute_b32 v177, v165, v176
	s_waitcnt lgkmcnt(3)
	v_add_f32_e32 v180, v180, v181
	ds_bpermute_b32 v181, v165, v180
	s_waitcnt lgkmcnt(3)
	v_add_f32_e32 v184, v184, v185
	ds_bpermute_b32 v185, v165, v184
	s_waitcnt lgkmcnt(3)
	v_add_f32_e32 v192, v192, v193
	ds_bpermute_b32 v193, v165, v192
	s_waitcnt lgkmcnt(3)
	v_add_f32_e32 v176, v176, v177
	s_waitcnt lgkmcnt(2)
	v_add_f32_e32 v180, v180, v181
	s_waitcnt lgkmcnt(1)
	v_add_f32_e32 v184, v184, v185
	s_waitcnt lgkmcnt(0)
	v_add_f32_e32 v192, v192, v193
	v_fmamk_f32 v176, v176, 0x3a800000, v223
	v_fmamk_f32 v180, v180, 0x3a800000, v223
	v_fmamk_f32 v184, v184, 0x3a800000, v223
	v_fmamk_f32 v192, v192, 0x3a800000, v223
	v_rsq_f32_e32 v167, v176
	v_rsq_f32_e32 v161, v180
	v_rsq_f32_e32 v159, v184
	v_rsq_f32_e32 v157, v192
	v_mov_b32_e32 v176, v197
	v_mov_b32_e32 v177, v198
	v_mov_b32_e32 v197, v199
	v_pk_add_f32 v[176:177], v[176:177], v[196:197]
	s_nop 0
	v_add_f32_e32 v155, v176, v177
	v_mov_b32_e32 v176, v139
	v_mov_b32_e32 v177, v140
	v_mov_b32_e32 v139, v141
	v_mov_b32_e32 v140, v135
	v_mov_b32_e32 v141, v136
	v_mov_b32_e32 v135, v137
	v_mov_b32_e32 v136, v131
	v_mov_b32_e32 v137, v132
	v_mov_b32_e32 v131, v133
	v_pk_add_f32 v[134:135], v[140:141], v[134:135]
	v_pk_add_f32 v[130:131], v[136:137], v[130:131]
	v_add_f32_e32 v134, v134, v135
	v_add_f32_e32 v130, v130, v131
	ds_bpermute_b32 v135, v163, v134
	ds_bpermute_b32 v131, v163, v130
	ds_bpermute_b32 v169, v163, v155
	v_mul_f32_e32 v140, 0xbfb8aa3b, v167
	v_pk_add_f32 v[138:139], v[176:177], v[138:139]
	s_waitcnt lgkmcnt(2)
	v_add_f32_e32 v134, v134, v135
	s_waitcnt lgkmcnt(1)
	v_add_f32_e32 v130, v130, v131
	v_lshlrev_b64 v[132:133], 1, v[170:171]
	v_pk_mul_f32 v[170:171], v[128:129], v[140:141] op_sel_hi:[1,0]
	v_pk_mul_f32 v[176:177], v[126:127], v[140:141] op_sel_hi:[1,0]
	ds_bpermute_b32 v135, v165, v134
	ds_bpermute_b32 v131, v165, v130
	v_pk_mul_f32 v[178:179], v[124:125], v[140:141] op_sel_hi:[1,0]
	v_pk_mul_f32 v[140:141], v[122:123], v[140:141] op_sel_hi:[1,0]
	v_exp_f32_e32 v176, v176
	v_exp_f32_e32 v177, v177
	v_exp_f32_e32 v170, v170
	v_exp_f32_e32 v171, v171
	v_exp_f32_e32 v140, v140
	v_exp_f32_e32 v141, v141
	v_exp_f32_e32 v178, v178
	v_exp_f32_e32 v179, v179
	s_waitcnt lgkmcnt(2)
	v_add_f32_e32 v155, v155, v169
	ds_bpermute_b32 v169, v165, v155
	v_pk_add_f32 v[170:171], v[170:171], 1.0 op_sel_hi:[1,0]
	v_pk_add_f32 v[176:177], v[176:177], 1.0 op_sel_hi:[1,0]
	s_waitcnt lgkmcnt(2)
	v_add_f32_e32 v134, v134, v135
	s_waitcnt lgkmcnt(1)
	v_add_f32_e32 v130, v130, v131
	v_pk_add_f32 v[178:179], v[178:179], 1.0 op_sel_hi:[1,0]
	v_pk_add_f32 v[140:141], v[140:141], 1.0 op_sel_hi:[1,0]
	v_rcp_f32_e32 v122, v176
	v_rcp_f32_e32 v123, v177
	v_rcp_f32_e32 v124, v170
	v_rcp_f32_e32 v125, v171
	v_fmamk_f32 v134, v134, 0x3a800000, v223
	v_fmamk_f32 v130, v130, 0x3a800000, v223
	v_rcp_f32_e32 v126, v140
	v_rcp_f32_e32 v127, v141
	v_rcp_f32_e32 v128, v178
	v_rcp_f32_e32 v129, v179
	v_rsq_f32_e32 v135, v134
	v_rsq_f32_e32 v134, v130
	v_mov_b64_e32 v[130:131], s[10:11]
	v_mad_i64_i32 v[136:137], s[22:23], v168, s57, v[130:131]
	v_mul_f32_e32 v168, v167, v167
	s_waitcnt lgkmcnt(0)
	v_pk_mul_f32 v[122:123], v[168:169], v[122:123] op_sel_hi:[0,1]
	v_pk_mul_f32 v[124:125], v[168:169], v[124:125] op_sel_hi:[0,1]
	v_pk_mul_f32 v[120:121], v[120:121], v[124:125]
	v_pk_mul_f32 v[118:119], v[118:119], v[122:123]
	v_pk_mul_f32 v[122:123], v[168:169], v[126:127] op_sel_hi:[0,1]
	v_pk_mul_f32 v[124:125], v[168:169], v[128:129] op_sel_hi:[0,1]
	v_pk_mul_f32 v[124:125], v[116:117], v[124:125]
	v_pk_mul_f32 v[116:117], v[114:115], v[122:123]
	v_lshl_add_u64 v[136:137], v[136:137], 0, v[132:133]
	v_cvt_pk_bf16_f32 v114, v118, v119
	v_cvt_pk_bf16_f32 v115, v120, v121
	v_cvt_pk_bf16_f32 v116, v116, v117
	v_cvt_pk_bf16_f32 v117, v124, v125
	global_store_dwordx4 v[136:137], v[114:117], off
	v_mul_f32_e32 v118, v161, v161
	v_add_f32_e32 v155, v155, v169
	v_mul_f32_e32 v116, 0xbfb8aa3b, v161
	v_pk_mul_f32 v[120:121], v[112:113], v[116:117] op_sel_hi:[1,0]
	v_pk_mul_f32 v[122:123], v[110:111], v[116:117] op_sel_hi:[1,0]
	v_pk_mul_f32 v[124:125], v[108:109], v[116:117] op_sel_hi:[1,0]
	v_pk_mul_f32 v[116:117], v[106:107], v[116:117] op_sel_hi:[1,0]
	v_exp_f32_e32 v122, v122
	v_exp_f32_e32 v123, v123
	v_exp_f32_e32 v120, v120
	v_exp_f32_e32 v121, v121
	v_exp_f32_e32 v116, v116
	v_exp_f32_e32 v117, v117
	v_exp_f32_e32 v124, v124
	v_exp_f32_e32 v125, v125
	v_pk_add_f32 v[120:121], v[120:121], 1.0 op_sel_hi:[1,0]
	v_pk_add_f32 v[122:123], v[122:123], 1.0 op_sel_hi:[1,0]
	v_pk_add_f32 v[116:117], v[116:117], 1.0 op_sel_hi:[1,0]
	v_pk_add_f32 v[124:125], v[124:125], 1.0 op_sel_hi:[1,0]
	v_rcp_f32_e32 v106, v122
	v_rcp_f32_e32 v107, v123
	v_rcp_f32_e32 v108, v120
	v_rcp_f32_e32 v109, v121
	v_rcp_f32_e32 v110, v116
	v_rcp_f32_e32 v111, v117
	v_rcp_f32_e32 v112, v124
	v_rcp_f32_e32 v113, v125
	v_pk_mul_f32 v[106:107], v[118:119], v[106:107] op_sel_hi:[0,1]
	v_pk_mul_f32 v[108:109], v[118:119], v[108:109] op_sel_hi:[0,1]
	v_pk_mul_f32 v[104:105], v[104:105], v[108:109]
	v_pk_mul_f32 v[102:103], v[102:103], v[106:107]
	v_pk_mul_f32 v[106:107], v[118:119], v[110:111] op_sel_hi:[0,1]
	v_pk_mul_f32 v[108:109], v[118:119], v[112:113] op_sel_hi:[0,1]
	v_mad_i64_i32 v[114:115], s[22:23], v166, s57, v[130:131]
	v_pk_mul_f32 v[108:109], v[100:101], v[108:109]
	v_pk_mul_f32 v[100:101], v[98:99], v[106:107]
	v_lshl_add_u64 v[114:115], v[114:115], 0, v[132:133]
	v_cvt_pk_bf16_f32 v98, v102, v103
	v_cvt_pk_bf16_f32 v99, v104, v105
	v_cvt_pk_bf16_f32 v100, v100, v101
	v_cvt_pk_bf16_f32 v101, v108, v109
	global_store_dwordx4 v[114:115], v[98:101], off
	v_mul_f32_e32 v102, v159, v159
	v_fmamk_f32 v155, v155, 0x3a800000, v223
	v_mul_f32_e32 v100, 0xbfb8aa3b, v159
	v_pk_mul_f32 v[104:105], v[96:97], v[100:101] op_sel_hi:[1,0]
	v_pk_mul_f32 v[106:107], v[94:95], v[100:101] op_sel_hi:[1,0]
	v_pk_mul_f32 v[108:109], v[92:93], v[100:101] op_sel_hi:[1,0]
	v_pk_mul_f32 v[100:101], v[90:91], v[100:101] op_sel_hi:[1,0]
	v_exp_f32_e32 v106, v106
	v_exp_f32_e32 v107, v107
	v_exp_f32_e32 v104, v104
	v_exp_f32_e32 v105, v105
	v_exp_f32_e32 v100, v100
	v_exp_f32_e32 v101, v101
	v_exp_f32_e32 v108, v108
	v_exp_f32_e32 v109, v109
	v_pk_add_f32 v[104:105], v[104:105], 1.0 op_sel_hi:[1,0]
	v_pk_add_f32 v[106:107], v[106:107], 1.0 op_sel_hi:[1,0]
	v_pk_add_f32 v[100:101], v[100:101], 1.0 op_sel_hi:[1,0]
	v_pk_add_f32 v[108:109], v[108:109], 1.0 op_sel_hi:[1,0]
	v_rcp_f32_e32 v90, v106
	v_rcp_f32_e32 v91, v107
	v_rcp_f32_e32 v92, v104
	v_rcp_f32_e32 v93, v105
	v_rcp_f32_e32 v94, v100
	v_rcp_f32_e32 v95, v101
	v_rcp_f32_e32 v96, v108
	v_rcp_f32_e32 v97, v109
	v_pk_mul_f32 v[90:91], v[102:103], v[90:91] op_sel_hi:[0,1]
	v_pk_mul_f32 v[92:93], v[102:103], v[92:93] op_sel_hi:[0,1]
	v_pk_mul_f32 v[88:89], v[88:89], v[92:93]
	v_pk_mul_f32 v[86:87], v[86:87], v[90:91]
	v_pk_mul_f32 v[90:91], v[102:103], v[94:95] op_sel_hi:[0,1]
	v_pk_mul_f32 v[92:93], v[102:103], v[96:97] op_sel_hi:[0,1]
	v_mad_i64_i32 v[98:99], s[22:23], v164, s57, v[130:131]
	v_pk_mul_f32 v[92:93], v[84:85], v[92:93]
	v_pk_mul_f32 v[84:85], v[82:83], v[90:91]
	v_lshl_add_u64 v[98:99], v[98:99], 0, v[132:133]
	v_cvt_pk_bf16_f32 v82, v86, v87
	v_cvt_pk_bf16_f32 v83, v88, v89
	v_cvt_pk_bf16_f32 v84, v84, v85
	v_cvt_pk_bf16_f32 v85, v92, v93
	global_store_dwordx4 v[98:99], v[82:85], off
	v_mul_f32_e32 v86, v157, v157
	v_rsq_f32_e32 v155, v155
	v_mul_f32_e32 v84, 0xbfb8aa3b, v157
	v_pk_mul_f32 v[88:89], v[80:81], v[84:85] op_sel_hi:[1,0]
	v_pk_mul_f32 v[90:91], v[78:79], v[84:85] op_sel_hi:[1,0]
	v_pk_mul_f32 v[92:93], v[76:77], v[84:85] op_sel_hi:[1,0]
	v_pk_mul_f32 v[84:85], v[74:75], v[84:85] op_sel_hi:[1,0]
	v_exp_f32_e32 v90, v90
	v_exp_f32_e32 v91, v91
	v_exp_f32_e32 v88, v88
	v_exp_f32_e32 v89, v89
	v_exp_f32_e32 v84, v84
	v_exp_f32_e32 v85, v85
	v_exp_f32_e32 v92, v92
	v_exp_f32_e32 v93, v93
	v_pk_add_f32 v[88:89], v[88:89], 1.0 op_sel_hi:[1,0]
	v_pk_add_f32 v[90:91], v[90:91], 1.0 op_sel_hi:[1,0]
	v_pk_add_f32 v[84:85], v[84:85], 1.0 op_sel_hi:[1,0]
	v_pk_add_f32 v[92:93], v[92:93], 1.0 op_sel_hi:[1,0]
	v_rcp_f32_e32 v74, v90
	v_rcp_f32_e32 v75, v91
	v_rcp_f32_e32 v76, v88
	v_rcp_f32_e32 v77, v89
	v_rcp_f32_e32 v78, v84
	v_rcp_f32_e32 v79, v85
	v_rcp_f32_e32 v80, v92
	v_rcp_f32_e32 v81, v93
	v_pk_mul_f32 v[74:75], v[86:87], v[74:75] op_sel_hi:[0,1]
	v_pk_mul_f32 v[76:77], v[86:87], v[76:77] op_sel_hi:[0,1]
	v_add_f32_e32 v138, v138, v139
	v_pk_mul_f32 v[72:73], v[72:73], v[76:77]
	v_pk_mul_f32 v[70:71], v[70:71], v[74:75]
	v_pk_mul_f32 v[74:75], v[86:87], v[78:79] op_sel_hi:[0,1]
	v_pk_mul_f32 v[76:77], v[86:87], v[80:81] op_sel_hi:[0,1]
	ds_bpermute_b32 v139, v163, v138
	v_mad_i64_i32 v[82:83], s[22:23], v162, s57, v[130:131]
	v_pk_mul_f32 v[76:77], v[68:69], v[76:77]
	v_pk_mul_f32 v[68:69], v[66:67], v[74:75]
	v_lshl_add_u64 v[82:83], v[82:83], 0, v[132:133]
	v_cvt_pk_bf16_f32 v66, v70, v71
	v_cvt_pk_bf16_f32 v67, v72, v73
	v_cvt_pk_bf16_f32 v68, v68, v69
	v_cvt_pk_bf16_f32 v69, v76, v77
	global_store_dwordx4 v[82:83], v[66:69], off
	s_waitcnt lgkmcnt(0)
	v_add_f32_e32 v138, v138, v139
	ds_bpermute_b32 v139, v165, v138
	v_mul_f32_e32 v68, 0xbfb8aa3b, v155
	v_pk_mul_f32 v[72:73], v[64:65], v[68:69] op_sel_hi:[1,0]
	v_pk_mul_f32 v[74:75], v[62:63], v[68:69] op_sel_hi:[1,0]
	v_pk_mul_f32 v[76:77], v[60:61], v[68:69] op_sel_hi:[1,0]
	v_pk_mul_f32 v[68:69], v[58:59], v[68:69] op_sel_hi:[1,0]
	v_exp_f32_e32 v74, v74
	v_exp_f32_e32 v75, v75
	v_exp_f32_e32 v72, v72
	v_exp_f32_e32 v73, v73
	v_exp_f32_e32 v68, v68
	v_exp_f32_e32 v69, v69
	v_exp_f32_e32 v76, v76
	v_exp_f32_e32 v77, v77
	v_pk_add_f32 v[72:73], v[72:73], 1.0 op_sel_hi:[1,0]
	v_pk_add_f32 v[74:75], v[74:75], 1.0 op_sel_hi:[1,0]
	v_pk_add_f32 v[68:69], v[68:69], 1.0 op_sel_hi:[1,0]
	v_pk_add_f32 v[76:77], v[76:77], 1.0 op_sel_hi:[1,0]
	v_rcp_f32_e32 v58, v74
	v_rcp_f32_e32 v59, v75
	v_rcp_f32_e32 v60, v72
	v_rcp_f32_e32 v61, v73
	v_rcp_f32_e32 v62, v68
	v_rcp_f32_e32 v63, v69
	v_rcp_f32_e32 v64, v76
	v_rcp_f32_e32 v65, v77
	s_waitcnt lgkmcnt(0)
	v_add_f32_e32 v138, v138, v139
	v_fmamk_f32 v138, v138, 0x3a800000, v223
	v_mul_f32_e32 v70, v155, v155
	v_rsq_f32_e32 v138, v138
	v_pk_mul_f32 v[58:59], v[70:71], v[58:59] op_sel_hi:[0,1]
	v_pk_mul_f32 v[60:61], v[70:71], v[60:61] op_sel_hi:[0,1]
	v_pk_mul_f32 v[56:57], v[56:57], v[60:61]
	v_pk_mul_f32 v[54:55], v[54:55], v[58:59]
	v_pk_mul_f32 v[58:59], v[70:71], v[62:63] op_sel_hi:[0,1]
	v_pk_mul_f32 v[60:61], v[70:71], v[64:65] op_sel_hi:[0,1]
	v_mad_i64_i32 v[66:67], s[22:23], v160, s57, v[130:131]
	v_pk_mul_f32 v[60:61], v[52:53], v[60:61]
	v_pk_mul_f32 v[52:53], v[50:51], v[58:59]
	v_lshl_add_u64 v[66:67], v[66:67], 0, v[132:133]
	v_cvt_pk_bf16_f32 v50, v54, v55
	v_cvt_pk_bf16_f32 v51, v56, v57
	v_cvt_pk_bf16_f32 v52, v52, v53
	v_cvt_pk_bf16_f32 v53, v60, v61
	global_store_dwordx4 v[66:67], v[50:53], off
	v_mul_f32_e32 v54, v138, v138
	s_nop 0
	v_mul_f32_e32 v52, 0xbfb8aa3b, v138
	v_pk_mul_f32 v[56:57], v[48:49], v[52:53] op_sel_hi:[1,0]
	v_pk_mul_f32 v[58:59], v[46:47], v[52:53] op_sel_hi:[1,0]
	v_pk_mul_f32 v[60:61], v[44:45], v[52:53] op_sel_hi:[1,0]
	v_pk_mul_f32 v[52:53], v[42:43], v[52:53] op_sel_hi:[1,0]
	v_exp_f32_e32 v58, v58
	v_exp_f32_e32 v59, v59
	v_exp_f32_e32 v56, v56
	v_exp_f32_e32 v57, v57
	v_exp_f32_e32 v52, v52
	v_exp_f32_e32 v53, v53
	v_exp_f32_e32 v60, v60
	v_exp_f32_e32 v61, v61
	v_pk_add_f32 v[56:57], v[56:57], 1.0 op_sel_hi:[1,0]
	v_pk_add_f32 v[58:59], v[58:59], 1.0 op_sel_hi:[1,0]
	v_pk_add_f32 v[52:53], v[52:53], 1.0 op_sel_hi:[1,0]
	v_pk_add_f32 v[60:61], v[60:61], 1.0 op_sel_hi:[1,0]
	v_rcp_f32_e32 v42, v58
	v_rcp_f32_e32 v43, v59
	v_rcp_f32_e32 v44, v56
	v_rcp_f32_e32 v45, v57
	v_rcp_f32_e32 v46, v52
	v_rcp_f32_e32 v47, v53
	v_rcp_f32_e32 v48, v60
	v_rcp_f32_e32 v49, v61
	v_pk_mul_f32 v[42:43], v[54:55], v[42:43] op_sel_hi:[0,1]
	v_pk_mul_f32 v[44:45], v[54:55], v[44:45] op_sel_hi:[0,1]
	v_pk_mul_f32 v[40:41], v[40:41], v[44:45]
	v_pk_mul_f32 v[38:39], v[38:39], v[42:43]
	v_pk_mul_f32 v[42:43], v[54:55], v[46:47] op_sel_hi:[0,1]
	v_pk_mul_f32 v[44:45], v[54:55], v[48:49] op_sel_hi:[0,1]
	v_mad_i64_i32 v[50:51], s[22:23], v158, s57, v[130:131]
	v_pk_mul_f32 v[44:45], v[36:37], v[44:45]
	v_pk_mul_f32 v[36:37], v[34:35], v[42:43]
	v_lshl_add_u64 v[50:51], v[50:51], 0, v[132:133]
	v_cvt_pk_bf16_f32 v34, v38, v39
	v_cvt_pk_bf16_f32 v35, v40, v41
	v_cvt_pk_bf16_f32 v36, v36, v37
	v_cvt_pk_bf16_f32 v37, v44, v45
	global_store_dwordx4 v[50:51], v[34:37], off
	v_mul_f32_e32 v38, v135, v135
	s_nop 0
	v_mul_f32_e32 v36, 0xbfb8aa3b, v135
	v_pk_mul_f32 v[40:41], v[32:33], v[36:37] op_sel_hi:[1,0]
	v_pk_mul_f32 v[42:43], v[30:31], v[36:37] op_sel_hi:[1,0]
	v_pk_mul_f32 v[44:45], v[28:29], v[36:37] op_sel_hi:[1,0]
	v_pk_mul_f32 v[36:37], v[26:27], v[36:37] op_sel_hi:[1,0]
	v_exp_f32_e32 v42, v42
	v_exp_f32_e32 v43, v43
	v_exp_f32_e32 v40, v40
	v_exp_f32_e32 v41, v41
	v_exp_f32_e32 v36, v36
	v_exp_f32_e32 v37, v37
	v_exp_f32_e32 v44, v44
	v_exp_f32_e32 v45, v45
	v_pk_add_f32 v[40:41], v[40:41], 1.0 op_sel_hi:[1,0]
	v_pk_add_f32 v[42:43], v[42:43], 1.0 op_sel_hi:[1,0]
	v_pk_add_f32 v[36:37], v[36:37], 1.0 op_sel_hi:[1,0]
	v_pk_add_f32 v[44:45], v[44:45], 1.0 op_sel_hi:[1,0]
	v_rcp_f32_e32 v26, v42
	v_rcp_f32_e32 v27, v43
	v_rcp_f32_e32 v28, v40
	v_rcp_f32_e32 v29, v41
	v_rcp_f32_e32 v30, v36
	v_rcp_f32_e32 v31, v37
	v_rcp_f32_e32 v32, v44
	v_rcp_f32_e32 v33, v45
	v_pk_mul_f32 v[26:27], v[38:39], v[26:27] op_sel_hi:[0,1]
	v_pk_mul_f32 v[28:29], v[38:39], v[28:29] op_sel_hi:[0,1]
	v_pk_mul_f32 v[24:25], v[24:25], v[28:29]
	v_pk_mul_f32 v[22:23], v[22:23], v[26:27]
	v_pk_mul_f32 v[26:27], v[38:39], v[30:31] op_sel_hi:[0,1]
	v_pk_mul_f32 v[28:29], v[38:39], v[32:33] op_sel_hi:[0,1]
	v_mad_i64_i32 v[34:35], s[22:23], v156, s57, v[130:131]
	v_pk_mul_f32 v[28:29], v[20:21], v[28:29]
	v_pk_mul_f32 v[20:21], v[18:19], v[26:27]
	v_lshl_add_u64 v[34:35], v[34:35], 0, v[132:133]
	v_cvt_pk_bf16_f32 v18, v22, v23
	v_cvt_pk_bf16_f32 v19, v24, v25
	v_cvt_pk_bf16_f32 v20, v20, v21
	v_cvt_pk_bf16_f32 v21, v28, v29
	global_store_dwordx4 v[34:35], v[18:21], off
	v_mul_f32_e32 v22, v134, v134
	s_nop 0
	v_mul_f32_e32 v20, 0xbfb8aa3b, v134
	v_pk_mul_f32 v[24:25], v[16:17], v[20:21] op_sel_hi:[1,0]
	v_pk_mul_f32 v[26:27], v[14:15], v[20:21] op_sel_hi:[1,0]
	v_pk_mul_f32 v[28:29], v[12:13], v[20:21] op_sel_hi:[1,0]
	v_pk_mul_f32 v[20:21], v[10:11], v[20:21] op_sel_hi:[1,0]
	v_exp_f32_e32 v26, v26
	v_exp_f32_e32 v27, v27
	v_exp_f32_e32 v24, v24
	v_exp_f32_e32 v25, v25
	v_exp_f32_e32 v20, v20
	v_exp_f32_e32 v21, v21
	v_exp_f32_e32 v28, v28
	v_exp_f32_e32 v29, v29
	v_pk_add_f32 v[24:25], v[24:25], 1.0 op_sel_hi:[1,0]
	v_pk_add_f32 v[26:27], v[26:27], 1.0 op_sel_hi:[1,0]
	v_pk_add_f32 v[20:21], v[20:21], 1.0 op_sel_hi:[1,0]
	v_pk_add_f32 v[28:29], v[28:29], 1.0 op_sel_hi:[1,0]
	v_rcp_f32_e32 v10, v26
	v_rcp_f32_e32 v11, v27
	v_rcp_f32_e32 v12, v24
	v_rcp_f32_e32 v13, v25
	v_rcp_f32_e32 v14, v20
	v_rcp_f32_e32 v15, v21
	v_rcp_f32_e32 v16, v28
	v_rcp_f32_e32 v17, v29
	v_pk_mul_f32 v[10:11], v[22:23], v[10:11] op_sel_hi:[0,1]
	v_pk_mul_f32 v[12:13], v[22:23], v[12:13] op_sel_hi:[0,1]
	v_pk_mul_f32 v[8:9], v[8:9], v[12:13]
	v_pk_mul_f32 v[6:7], v[6:7], v[10:11]
	v_pk_mul_f32 v[10:11], v[22:23], v[14:15] op_sel_hi:[0,1]
	v_pk_mul_f32 v[12:13], v[22:23], v[16:17] op_sel_hi:[0,1]
	v_mad_i64_i32 v[18:19], s[22:23], v154, s57, v[130:131]
	v_pk_mul_f32 v[12:13], v[4:5], v[12:13]
	v_pk_mul_f32 v[4:5], v[2:3], v[10:11]
	v_lshl_add_u64 v[18:19], v[18:19], 0, v[132:133]
	v_cvt_pk_bf16_f32 v2, v6, v7
	v_cvt_pk_bf16_f32 v3, v8, v9
	v_cvt_pk_bf16_f32 v4, v4, v5
	v_cvt_pk_bf16_f32 v5, v12, v13
	s_mov_b64 s[22:23], -1
	global_store_dwordx4 v[18:19], v[2:5], off
	s_cbranch_vccnz .LBB0_286
	s_andn2_b64 vcc, exec, s[8:9]
	s_cbranch_vccnz .LBB0_285
	s_barrier
	s_branch .LBB0_285
